# DF softmax: |x| masks folded into the consuming v_fma as source modifiers (31 fewer VALU ops per step per wave)
# speedup vs baseline: 1.0022x; 1.0022x over previous
.LBB0_412:
	s_andn2_b64 vcc, exec, s[10:11]
	s_cbranch_vccnz .LBB0_414
	v_add_f32 v4, v0, s38
	v_add_f32 v5, v0, s39
	v_add_f32_e32 v3, -1.0, v0
	v_and_b32_e32 v2, 0x7fffffff, v0
	v_fma_f32 v2, s4, v2, v96
	v_fma_f32 v3, s5, |v3|, v97
	v_fma_f32 v6, s4, |v4|, v80
	v_fma_f32 v7, s5, |v5|, v81
	v_add_f32 v8, v0, s40
	v_add_f32 v9, v0, s41
	v_max_f32_e32 v4, v2, v6
	v_max_f32_e32 v5, v3, v7
	v_max3_f32 v10, v4, s82, v5
	v_add_f32 v4, v0, s36
	v_add_f32 v5, v0, s37
	v_fma_f32 v4, s4, |v4|, v98
	v_fma_f32 v5, s5, |v5|, v99
	v_fma_f32 v8, s4, |v8|, v82
	v_fma_f32 v9, s5, |v9|, v83
	v_mov_b32_e32 v238, 0
	v_max_f32_e32 v11, v4, v8
	v_max_f32_e32 v12, v5, v9
	v_max3_f32 v14, v10, v11, v12
	v_add_f32 v10, v0, s42
	v_add_f32 v11, v0, s43
	v_add_f32 v12, v0, s44
	v_add_f32 v13, v0, s45
	v_fma_f32 v10, s4, |v10|, v100
	v_fma_f32 v11, s5, |v11|, v101
	v_fma_f32 v12, s4, |v12|, v84
	v_fma_f32 v13, s5, |v13|, v85
	s_nop 0
	v_max_f32_e32 v15, v10, v12
	v_max_f32_e32 v80, v11, v13
	v_max3_f32 v82, v14, v15, v80
	v_add_f32 v14, v0, s46
	v_add_f32 v15, v0, s47
	v_add_f32 v80, v0, s48
	v_add_f32 v81, v0, s49
	v_fma_f32 v14, s4, |v14|, v102
	v_fma_f32 v15, s5, |v15|, v103
	v_fma_f32 v144, s4, |v80|, v86
	v_fma_f32 v145, s5, |v81|, v87
	s_nop 0
	v_max_f32_e32 v80, v14, v144
	v_max_f32_e32 v81, v15, v145
	v_max3_f32 v84, v82, v80, v81
	v_add_f32 v80, v0, s50
	v_add_f32 v81, v0, s51
	v_add_f32 v82, v0, s52
	v_add_f32 v83, v0, s53
	v_fma_f32 v146, s4, |v80|, v104
	v_fma_f32 v147, s5, |v81|, v105
	v_fma_f32 v202, s4, |v82|, v88
	v_fma_f32 v203, s5, |v83|, v89
	v_add_f32 v82, v0, s58
	v_add_f32 v83, v0, s59
	v_max_f32_e32 v80, v146, v202
	v_max_f32_e32 v81, v147, v203
	v_max3_f32 v84, v84, v80, v81
	v_add_f32 v80, v0, s54
	v_add_f32 v81, v0, s55
	v_fma_f32 v204, s4, |v80|, v106
	v_fma_f32 v205, s5, |v81|, v107
	v_fma_f32 v206, s4, |v82|, v90
	v_fma_f32 v207, s5, |v83|, v91
	v_add_f32 v82, v0, s62
	v_add_f32 v83, v0, s63
	v_max_f32_e32 v80, v204, v206
	v_max_f32_e32 v81, v205, v207
	v_max3_f32 v84, v84, v80, v81
	v_add_f32 v80, v0, s60
	v_add_f32 v81, v0, s61
	v_fma_f32 v208, s4, |v80|, v108
	v_fma_f32 v209, s5, |v81|, v109
	v_fma_f32 v210, s4, |v82|, v92
	v_fma_f32 v211, s5, |v83|, v93
	v_add_f32 v82, v0, s66
	v_add_f32 v83, v0, s67
	v_max_f32_e32 v80, v208, v210
	v_max_f32_e32 v81, v209, v211
	v_max3_f32 v84, v84, v80, v81
	v_add_f32 v80, v0, s64
	v_add_f32 v81, v0, s65
	v_fma_f32 v212, s4, |v80|, v110
	v_fma_f32 v213, s5, |v81|, v111
	v_fma_f32 v214, s4, |v82|, v94
	v_fma_f32 v215, s5, |v83|, v95
	s_nop 0
	v_max_f32_e32 v0, v212, v214
	v_max_f32_e32 v80, v213, v215
	v_max3_f32 v239, v84, v0, v80

.LBB0_441:
	s_andn2_b64 vcc, exec, s[8:9]
	s_cbranch_vccnz .LBB0_443
	v_add_f32_e32 v15, -1.0, v0
	v_add_f32 v148, v0, s38
	v_add_f32 v149, v0, s39
	v_and_b32_e32 v15, 0x7fffffff, v15
	v_fma_f32 v14, s4, |v0|, v96
	v_fma_f32 v15, s5, v15, v97
	v_fma_f32 v186, s4, |v148|, v80
	v_fma_f32 v187, s5, |v149|, v81
	v_add_f32 v96, v0, s40
	v_add_f32 v97, v0, s41
	v_max_f32_e32 v80, v14, v186
	v_max_f32_e32 v81, v15, v187
	v_max3_f32 v148, v80, s82, v81
	v_add_f32 v80, v0, s36
	v_add_f32 v81, v0, s37
	v_fma_f32 v184, s4, |v80|, v98
	v_fma_f32 v185, s5, |v81|, v99
	v_fma_f32 v188, s4, |v96|, v82
	v_fma_f32 v189, s5, |v97|, v83
	v_add_f32 v82, v0, s44
	v_add_f32 v83, v0, s45
	v_max_f32_e32 v80, v184, v188
	v_max_f32_e32 v81, v185, v189
	v_max3_f32 v96, v148, v80, v81
	v_add_f32 v80, v0, s42
	v_add_f32 v81, v0, s43
	v_fma_f32 v190, s4, |v80|, v100
	v_fma_f32 v191, s5, |v81|, v101
	v_fma_f32 v192, s4, |v82|, v84
	v_fma_f32 v193, s5, |v83|, v85
	v_add_f32 v82, v0, s48
	v_add_f32 v83, v0, s49
	v_max_f32_e32 v80, v190, v192
	v_max_f32_e32 v81, v191, v193
	v_max3_f32 v84, v96, v80, v81
	v_add_f32 v80, v0, s46
	v_add_f32 v81, v0, s47
	v_fma_f32 v194, s4, |v80|, v102
	v_fma_f32 v195, s5, |v81|, v103
	v_fma_f32 v198, s4, |v82|, v86
	v_fma_f32 v199, s5, |v83|, v87
	v_add_f32 v82, v0, s52
	v_add_f32 v83, v0, s53
	v_max_f32_e32 v80, v194, v198
	v_max_f32_e32 v81, v195, v199
	v_max3_f32 v84, v84, v80, v81
	v_add_f32 v80, v0, s50
	v_add_f32 v81, v0, s51
	v_fma_f32 v200, s4, |v80|, v104
	v_fma_f32 v201, s5, |v81|, v105
	v_fma_f32 v202, s4, |v82|, v88
	v_fma_f32 v203, s5, |v83|, v89
	v_add_f32 v82, v0, s58
	v_add_f32 v83, v0, s59
	v_max_f32_e32 v80, v200, v202
	v_max_f32_e32 v81, v201, v203
	v_max3_f32 v84, v84, v80, v81
	v_add_f32 v80, v0, s54
	v_add_f32 v81, v0, s55
	v_fma_f32 v204, s4, |v80|, v106
	v_fma_f32 v205, s5, |v81|, v107
	v_fma_f32 v206, s4, |v82|, v90
	v_fma_f32 v207, s5, |v83|, v91
	v_add_f32 v82, v0, s62
	v_add_f32 v83, v0, s63
	v_max_f32_e32 v80, v204, v206
	v_max_f32_e32 v81, v205, v207
	v_max3_f32 v84, v84, v80, v81
	v_add_f32 v80, v0, s60
	v_add_f32 v81, v0, s61
	v_fma_f32 v208, s4, |v80|, v108
	v_fma_f32 v209, s5, |v81|, v109
	v_fma_f32 v210, s4, |v82|, v92
	v_fma_f32 v211, s5, |v83|, v93
	v_add_f32 v82, v0, s66
	v_add_f32 v83, v0, s67
	v_max_f32_e32 v80, v208, v210
	v_max_f32_e32 v81, v209, v211
	v_max3_f32 v84, v84, v80, v81
	v_add_f32 v80, v0, s64
	v_add_f32 v81, v0, s65
	v_fma_f32 v212, s4, |v80|, v110
	v_fma_f32 v213, s5, |v81|, v111
	v_fma_f32 v214, s4, |v82|, v94
	v_fma_f32 v215, s5, |v83|, v95
	v_mov_b32_e32 v236, 0
	v_max_f32_e32 v0, v212, v214
	v_max_f32_e32 v80, v213, v215
	v_max3_f32 v237, v84, v0, v80
